# P7 gate/up GEMM: tile epilogues no longer re-align the two wave halves (barrier pair around the epilogue removed, one catch-up barrier at phase end)
# baseline (speedup 1.0000x reference)
.LBB0_881:
	ds_read_b128 v[150:153], v147
	ds_read_b128 v[154:157], v147 offset:1024
	ds_read_b128 v[158:161], v147 offset:2048
	ds_read_b128 v[162:165], v147 offset:3072
	ds_read_b128 v[166:169], v148
	ds_read_b128 v[170:173], v148 offset:1024
	ds_read_b128 v[174:177], v148 offset:2048
	ds_read_b128 v[178:181], v148 offset:3072
	s_add_u32 s20, s18, 0xfffc0080
	s_addc_u32 s21, s19, -1
	s_cmp_eq_u32 s44, 12
	s_cselect_b32 s23, s11, s21
	s_cselect_b32 s22, s40, s20
	s_cselect_b32 s21, s9, s43
	s_cselect_b32 s20, s41, s42
	v_lshl_add_u64 v[194:195], s[18:19], 0, v[136:137]
	s_add_i32 m0, s17, 0xc000
	ds_read_b128 v[182:185], v149
	ds_read_b128 v[186:189], v149 offset:1024
	ds_read_b128 v[190:193], v149 offset:2048
	ds_read_b128 v[200:203], v149 offset:3072
	ds_read_b128 v[204:207], v149 offset:4096
	ds_read_b128 v[208:211], v149 offset:5120
	ds_read_b128 v[212:215], v149 offset:6144
	ds_read_b128 v[216:219], v149 offset:7168
	global_load_lds_dwordx4 v[194:195], off
	v_lshl_add_u64 v[194:195], s[18:19], 0, v[138:139]
	s_add_i32 m0, s17, 0xe000
	s_nop 0
	global_load_lds_dwordx4 v[194:195], off
	s_waitcnt vmcnt(8)
	s_waitcnt lgkmcnt(0)
	s_barrier
	s_setprio 1
	s_waitcnt lgkmcnt(0)
	v_mfma_f32_16x16x32_bf16 v[124:127], v[150:153], v[182:185], v[124:127]
	v_mfma_f32_16x16x32_bf16 v[120:123], v[158:161], v[182:185], v[120:123]
	v_mfma_f32_16x16x32_bf16 v[108:111], v[150:153], v[190:193], v[108:111]
	v_mfma_f32_16x16x32_bf16 v[104:107], v[158:161], v[190:193], v[104:107]
	v_mfma_f32_16x16x32_bf16 v[92:95], v[150:153], v[204:207], v[92:95]
	v_mfma_f32_16x16x32_bf16 v[88:91], v[158:161], v[204:207], v[88:91]
	v_mfma_f32_16x16x32_bf16 v[76:79], v[150:153], v[212:215], v[76:79]
	v_mfma_f32_16x16x32_bf16 v[72:75], v[158:161], v[212:215], v[72:75]
	v_mfma_f32_16x16x32_bf16 v[124:127], v[154:157], v[186:189], v[124:127]
	v_mfma_f32_16x16x32_bf16 v[120:123], v[162:165], v[186:189], v[120:123]
	v_mfma_f32_16x16x32_bf16 v[108:111], v[154:157], v[200:203], v[108:111]
	v_mfma_f32_16x16x32_bf16 v[104:107], v[162:165], v[200:203], v[104:107]
	v_mfma_f32_16x16x32_bf16 v[92:95], v[154:157], v[208:211], v[92:95]
	v_mfma_f32_16x16x32_bf16 v[88:91], v[162:165], v[208:211], v[88:91]
	v_mfma_f32_16x16x32_bf16 v[76:79], v[154:157], v[216:219], v[76:79]
	v_mfma_f32_16x16x32_bf16 v[72:75], v[162:165], v[216:219], v[72:75]
	s_setprio 0
	s_setprio 1
	v_mfma_f32_16x16x32_bf16 v[116:119], v[166:169], v[182:185], v[116:119]
	v_mfma_f32_16x16x32_bf16 v[112:115], v[174:177], v[182:185], v[112:115]
	v_mfma_f32_16x16x32_bf16 v[100:103], v[166:169], v[190:193], v[100:103]
	v_mfma_f32_16x16x32_bf16 v[96:99], v[174:177], v[190:193], v[96:99]
	v_mfma_f32_16x16x32_bf16 v[84:87], v[166:169], v[204:207], v[84:87]
	v_mfma_f32_16x16x32_bf16 v[80:83], v[174:177], v[204:207], v[80:83]
	v_mfma_f32_16x16x32_bf16 v[68:71], v[166:169], v[212:215], v[68:71]
	v_mfma_f32_16x16x32_bf16 v[64:67], v[174:177], v[212:215], v[64:67]
	v_mfma_f32_16x16x32_bf16 v[116:119], v[170:173], v[186:189], v[116:119]
	v_mfma_f32_16x16x32_bf16 v[112:115], v[178:181], v[186:189], v[112:115]
	v_mfma_f32_16x16x32_bf16 v[100:103], v[170:173], v[200:203], v[100:103]
	v_mfma_f32_16x16x32_bf16 v[96:99], v[178:181], v[200:203], v[96:99]
	v_mfma_f32_16x16x32_bf16 v[84:87], v[170:173], v[208:211], v[84:87]
	v_mfma_f32_16x16x32_bf16 v[80:83], v[178:181], v[208:211], v[80:83]
	v_mfma_f32_16x16x32_bf16 v[68:71], v[170:173], v[216:219], v[68:71]
	v_mfma_f32_16x16x32_bf16 v[64:67], v[178:181], v[216:219], v[64:67]
	s_setprio 0
	s_barrier
	s_add_i32 s45, s36, s24
	v_lshl_add_u64 v[194:195], s[20:21], 0, v[132:133]
	s_mov_b32 m0, s45
	ds_read_b128 v[182:185], v149 offset:16384
	ds_read_b128 v[186:189], v149 offset:17408
	ds_read_b128 v[190:193], v149 offset:18432
	ds_read_b128 v[200:203], v149 offset:19456
	ds_read_b128 v[204:207], v149 offset:20480
	ds_read_b128 v[208:211], v149 offset:21504
	ds_read_b128 v[212:215], v149 offset:22528
	ds_read_b128 v[216:219], v149 offset:23552
	global_load_lds_dwordx4 v[194:195], off
	s_add_i32 m0, s45, 0x2000
	s_add_u32 s46, s20, 0x40000
	v_lshl_add_u64 v[220:221], s[20:21], 0, v[128:129]
	s_addc_u32 s47, s21, 0
	s_add_i32 s45, s37, s24
	global_load_lds_dwordx4 v[220:221], off
	v_lshl_add_u64 v[222:223], s[46:47], 0, v[132:133]
	s_mov_b32 m0, s45
	v_lshl_add_u64 v[224:225], s[22:23], 0, v[130:131]
	global_load_lds_dwordx4 v[222:223], off
	v_lshl_add_u64 v[222:223], s[46:47], 0, v[128:129]
	s_add_i32 m0, s45, 0x2000
	s_nop 0
	global_load_lds_dwordx4 v[222:223], off
	v_lshl_add_u64 v[222:223], s[22:23], 0, v[134:135]
	s_mov_b32 m0, s17
	s_nop 0
	global_load_lds_dwordx4 v[222:223], off
	s_mov_b32 m0, s27
	s_nop 0
	global_load_lds_dwordx4 v[224:225], off
	s_waitcnt vmcnt(8)
	s_waitcnt lgkmcnt(0)
	s_barrier
	s_setprio 1
	s_waitcnt lgkmcnt(0)
	v_mfma_f32_16x16x32_bf16 v[60:63], v[150:153], v[182:185], v[60:63]
	v_mfma_f32_16x16x32_bf16 v[56:59], v[158:161], v[182:185], v[56:59]
	v_mfma_f32_16x16x32_bf16 v[44:47], v[150:153], v[190:193], v[44:47]
	v_mfma_f32_16x16x32_bf16 v[40:43], v[158:161], v[190:193], v[40:43]
	v_mfma_f32_16x16x32_bf16 v[28:31], v[150:153], v[204:207], v[28:31]
	v_mfma_f32_16x16x32_bf16 v[24:27], v[158:161], v[204:207], v[24:27]
	v_mfma_f32_16x16x32_bf16 v[12:15], v[150:153], v[212:215], v[12:15]
	v_mfma_f32_16x16x32_bf16 v[8:11], v[158:161], v[212:215], v[8:11]
	v_mfma_f32_16x16x32_bf16 v[60:63], v[154:157], v[186:189], v[60:63]
	v_mfma_f32_16x16x32_bf16 v[56:59], v[162:165], v[186:189], v[56:59]
	v_mfma_f32_16x16x32_bf16 v[44:47], v[154:157], v[200:203], v[44:47]
	v_mfma_f32_16x16x32_bf16 v[40:43], v[162:165], v[200:203], v[40:43]
	v_mfma_f32_16x16x32_bf16 v[28:31], v[154:157], v[208:211], v[28:31]
	v_mfma_f32_16x16x32_bf16 v[24:27], v[162:165], v[208:211], v[24:27]
	v_mfma_f32_16x16x32_bf16 v[12:15], v[154:157], v[216:219], v[12:15]
	v_mfma_f32_16x16x32_bf16 v[8:11], v[162:165], v[216:219], v[8:11]
	s_setprio 0
	s_setprio 1
	v_mfma_f32_16x16x32_bf16 v[52:55], v[166:169], v[182:185], v[52:55]
	v_mfma_f32_16x16x32_bf16 v[48:51], v[174:177], v[182:185], v[48:51]
	v_mfma_f32_16x16x32_bf16 v[36:39], v[166:169], v[190:193], v[36:39]
	v_mfma_f32_16x16x32_bf16 v[32:35], v[174:177], v[190:193], v[32:35]
	v_mfma_f32_16x16x32_bf16 v[20:23], v[166:169], v[204:207], v[20:23]
	v_mfma_f32_16x16x32_bf16 v[16:19], v[174:177], v[204:207], v[16:19]
	v_mfma_f32_16x16x32_bf16 v[4:7], v[166:169], v[212:215], v[4:7]
	v_mfma_f32_16x16x32_bf16 v[0:3], v[174:177], v[212:215], v[0:3]
	v_mfma_f32_16x16x32_bf16 v[52:55], v[170:173], v[186:189], v[52:55]
	v_mfma_f32_16x16x32_bf16 v[48:51], v[178:181], v[186:189], v[48:51]
	v_mfma_f32_16x16x32_bf16 v[36:39], v[170:173], v[200:203], v[36:39]
	v_mfma_f32_16x16x32_bf16 v[32:35], v[178:181], v[200:203], v[32:35]
	v_mfma_f32_16x16x32_bf16 v[20:23], v[170:173], v[208:211], v[20:23]
	v_mfma_f32_16x16x32_bf16 v[16:19], v[178:181], v[208:211], v[16:19]
	v_mfma_f32_16x16x32_bf16 v[4:7], v[170:173], v[216:219], v[4:7]
	v_mfma_f32_16x16x32_bf16 v[0:3], v[178:181], v[216:219], v[0:3]
	s_setprio 0
	s_barrier
	s_add_i32 s45, 0, 0x18000
	s_add_i32 s46, 0, 0x1c000
	v_add_u32_e32 v162, s45, v145
	v_add_u32_e32 v178, s46, v145
	ds_read_b128 v[150:153], v162
	ds_read_b128 v[154:157], v162 offset:1024
	ds_read_b128 v[158:161], v162 offset:2048
	ds_read_b128 v[162:165], v162 offset:3072
	ds_read_b128 v[166:169], v178
	ds_read_b128 v[170:173], v178 offset:1024
	ds_read_b128 v[174:177], v178 offset:2048
	ds_read_b128 v[178:181], v178 offset:3072
	s_add_u32 s22, s22, 0x40000
	s_addc_u32 s23, s23, 0
	s_mov_b32 m0, s28
	v_lshl_add_u64 v[226:227], s[22:23], 0, v[134:135]
	ds_read_b128 v[182:185], v149 offset:32768
	ds_read_b128 v[186:189], v149 offset:33792
	ds_read_b128 v[190:193], v149 offset:34816
	ds_read_b128 v[200:203], v149 offset:35840
	ds_read_b128 v[204:207], v149 offset:36864
	ds_read_b128 v[208:211], v149 offset:37888
	ds_read_b128 v[212:215], v149 offset:38912
	ds_read_b128 v[216:219], v149 offset:39936
	global_load_lds_dwordx4 v[226:227], off
	v_lshl_add_u64 v[226:227], s[22:23], 0, v[130:131]
	s_mov_b32 m0, s29
	s_nop 0
	global_load_lds_dwordx4 v[226:227], off
	s_waitcnt vmcnt(8)
	s_waitcnt lgkmcnt(0)
	s_barrier
	s_setprio 1
	s_waitcnt lgkmcnt(0)
	v_mfma_f32_16x16x32_bf16 v[124:127], v[150:153], v[182:185], v[124:127]
	v_mfma_f32_16x16x32_bf16 v[120:123], v[158:161], v[182:185], v[120:123]
	v_mfma_f32_16x16x32_bf16 v[108:111], v[150:153], v[190:193], v[108:111]
	v_mfma_f32_16x16x32_bf16 v[104:107], v[158:161], v[190:193], v[104:107]
	v_mfma_f32_16x16x32_bf16 v[92:95], v[150:153], v[204:207], v[92:95]
	v_mfma_f32_16x16x32_bf16 v[88:91], v[158:161], v[204:207], v[88:91]
	v_mfma_f32_16x16x32_bf16 v[76:79], v[150:153], v[212:215], v[76:79]
	v_mfma_f32_16x16x32_bf16 v[72:75], v[158:161], v[212:215], v[72:75]
	v_mfma_f32_16x16x32_bf16 v[124:127], v[154:157], v[186:189], v[124:127]
	v_mfma_f32_16x16x32_bf16 v[120:123], v[162:165], v[186:189], v[120:123]
	v_mfma_f32_16x16x32_bf16 v[108:111], v[154:157], v[200:203], v[108:111]
	v_mfma_f32_16x16x32_bf16 v[104:107], v[162:165], v[200:203], v[104:107]
	v_mfma_f32_16x16x32_bf16 v[92:95], v[154:157], v[208:211], v[92:95]
	v_mfma_f32_16x16x32_bf16 v[88:91], v[162:165], v[208:211], v[88:91]
	v_mfma_f32_16x16x32_bf16 v[76:79], v[154:157], v[216:219], v[76:79]
	v_mfma_f32_16x16x32_bf16 v[72:75], v[162:165], v[216:219], v[72:75]
	s_setprio 0
	s_setprio 1
	v_mfma_f32_16x16x32_bf16 v[116:119], v[166:169], v[182:185], v[116:119]
	v_mfma_f32_16x16x32_bf16 v[112:115], v[174:177], v[182:185], v[112:115]
	v_mfma_f32_16x16x32_bf16 v[100:103], v[166:169], v[190:193], v[100:103]
	v_mfma_f32_16x16x32_bf16 v[96:99], v[174:177], v[190:193], v[96:99]
	v_mfma_f32_16x16x32_bf16 v[84:87], v[166:169], v[204:207], v[84:87]
	v_mfma_f32_16x16x32_bf16 v[80:83], v[174:177], v[204:207], v[80:83]
	v_mfma_f32_16x16x32_bf16 v[68:71], v[166:169], v[212:215], v[68:71]
	v_mfma_f32_16x16x32_bf16 v[64:67], v[174:177], v[212:215], v[64:67]
	v_mfma_f32_16x16x32_bf16 v[116:119], v[170:173], v[186:189], v[116:119]
	v_mfma_f32_16x16x32_bf16 v[112:115], v[178:181], v[186:189], v[112:115]
	v_mfma_f32_16x16x32_bf16 v[100:103], v[170:173], v[200:203], v[100:103]
	v_mfma_f32_16x16x32_bf16 v[96:99], v[178:181], v[200:203], v[96:99]
	v_mfma_f32_16x16x32_bf16 v[84:87], v[170:173], v[208:211], v[84:87]
	v_mfma_f32_16x16x32_bf16 v[80:83], v[178:181], v[208:211], v[80:83]
	v_mfma_f32_16x16x32_bf16 v[68:71], v[170:173], v[216:219], v[68:71]
	v_mfma_f32_16x16x32_bf16 v[64:67], v[178:181], v[216:219], v[64:67]
	s_setprio 0
	s_barrier
	s_add_i32 s22, s45, s24
	v_lshl_add_u64 v[194:195], v[194:195], 0, s[4:5]
	s_mov_b32 m0, s22
	ds_read_b128 v[182:185], v149 offset:49152
	ds_read_b128 v[186:189], v149 offset:50176
	ds_read_b128 v[190:193], v149 offset:51200
	ds_read_b128 v[200:203], v149 offset:52224
	ds_read_b128 v[204:207], v149 offset:53248
	ds_read_b128 v[208:211], v149 offset:54272
	ds_read_b128 v[212:215], v149 offset:55296
	ds_read_b128 v[216:219], v149 offset:56320
	global_load_lds_dwordx4 v[194:195], off
	s_add_i32 m0, s22, 0x2000
	s_add_u32 s20, s20, 0x40080
	v_lshl_add_u64 v[194:195], v[220:221], 0, s[4:5]
	s_addc_u32 s21, s21, 0
	s_add_i32 s22, s46, s24
	global_load_lds_dwordx4 v[194:195], off
	v_lshl_add_u64 v[194:195], s[20:21], 0, v[132:133]
	s_mov_b32 m0, s22
	s_nop 0
	global_load_lds_dwordx4 v[194:195], off
	v_lshl_add_u64 v[194:195], s[20:21], 0, v[128:129]
	s_add_i32 m0, s22, 0x2000
	s_nop 0
	global_load_lds_dwordx4 v[194:195], off
	v_lshl_add_u64 v[194:195], v[222:223], 0, s[4:5]
	s_mov_b32 m0, s33
	s_nop 0
	global_load_lds_dwordx4 v[194:195], off
	v_lshl_add_u64 v[194:195], v[224:225], 0, s[4:5]
	s_mov_b32 m0, s34
	s_nop 0
	global_load_lds_dwordx4 v[194:195], off
	s_waitcnt vmcnt(8)
	s_waitcnt lgkmcnt(0)
	s_barrier
	s_setprio 1
	s_waitcnt lgkmcnt(0)
	v_mfma_f32_16x16x32_bf16 v[60:63], v[150:153], v[182:185], v[60:63]
	v_mfma_f32_16x16x32_bf16 v[56:59], v[158:161], v[182:185], v[56:59]
	v_mfma_f32_16x16x32_bf16 v[44:47], v[150:153], v[190:193], v[44:47]
	v_mfma_f32_16x16x32_bf16 v[40:43], v[158:161], v[190:193], v[40:43]
	v_mfma_f32_16x16x32_bf16 v[28:31], v[150:153], v[204:207], v[28:31]
	v_mfma_f32_16x16x32_bf16 v[24:27], v[158:161], v[204:207], v[24:27]
	v_mfma_f32_16x16x32_bf16 v[12:15], v[150:153], v[212:215], v[12:15]
	v_mfma_f32_16x16x32_bf16 v[8:11], v[158:161], v[212:215], v[8:11]
	v_mfma_f32_16x16x32_bf16 v[60:63], v[154:157], v[186:189], v[60:63]
	v_mfma_f32_16x16x32_bf16 v[56:59], v[162:165], v[186:189], v[56:59]
	v_mfma_f32_16x16x32_bf16 v[44:47], v[154:157], v[200:203], v[44:47]
	v_mfma_f32_16x16x32_bf16 v[40:43], v[162:165], v[200:203], v[40:43]
	v_mfma_f32_16x16x32_bf16 v[28:31], v[154:157], v[208:211], v[28:31]
	v_mfma_f32_16x16x32_bf16 v[24:27], v[162:165], v[208:211], v[24:27]
	v_mfma_f32_16x16x32_bf16 v[12:15], v[154:157], v[216:219], v[12:15]
	v_mfma_f32_16x16x32_bf16 v[8:11], v[162:165], v[216:219], v[8:11]
	s_setprio 0
	s_setprio 1
	v_mfma_f32_16x16x32_bf16 v[52:55], v[166:169], v[182:185], v[52:55]
	v_mfma_f32_16x16x32_bf16 v[48:51], v[174:177], v[182:185], v[48:51]
	v_mfma_f32_16x16x32_bf16 v[36:39], v[166:169], v[190:193], v[36:39]
	v_mfma_f32_16x16x32_bf16 v[32:35], v[174:177], v[190:193], v[32:35]
	v_mfma_f32_16x16x32_bf16 v[20:23], v[166:169], v[204:207], v[20:23]
	v_mfma_f32_16x16x32_bf16 v[16:19], v[174:177], v[204:207], v[16:19]
	v_mfma_f32_16x16x32_bf16 v[4:7], v[166:169], v[212:215], v[4:7]
	v_mfma_f32_16x16x32_bf16 v[0:3], v[174:177], v[212:215], v[0:3]
	v_mfma_f32_16x16x32_bf16 v[52:55], v[170:173], v[186:189], v[52:55]
	v_mfma_f32_16x16x32_bf16 v[48:51], v[178:181], v[186:189], v[48:51]
	v_mfma_f32_16x16x32_bf16 v[36:39], v[170:173], v[200:203], v[36:39]
	v_mfma_f32_16x16x32_bf16 v[32:35], v[178:181], v[200:203], v[32:35]
	v_mfma_f32_16x16x32_bf16 v[20:23], v[170:173], v[208:211], v[20:23]
	v_mfma_f32_16x16x32_bf16 v[16:19], v[178:181], v[208:211], v[16:19]
	v_mfma_f32_16x16x32_bf16 v[4:7], v[170:173], v[216:219], v[4:7]
	v_mfma_f32_16x16x32_bf16 v[0:3], v[178:181], v[216:219], v[0:3]
	s_setprio 0
	s_barrier
	s_add_i32 s44, s44, 2
	s_add_u32 s18, s18, 0x100
	s_addc_u32 s19, s19, 0
	s_add_u32 s42, s42, 0x100
	s_addc_u32 s43, s43, 0
	s_cmp_gt_u32 s44, 13
	s_cbranch_scc0 .LBB0_881
	s_and_b64 vcc, exec, s[6:7]
	s_cbranch_vccz .LBB0_884
	s_nop 0
.LBB0_884:
	v_mul_f32_e32 v151, 0xbfb8aa3b, v124
	v_exp_f32_e32 v151, v151
	v_mul_f32_e32 v152, 0xbfb8aa3b, v125
	v_exp_f32_e32 v153, v152
	v_lshl_or_b32 v152, s39, 7, v146
	v_add_f32_e32 v151, 1.0, v151
	v_rcp_f32_e32 v151, v151
	v_add_f32_e32 v153, 1.0, v153
	v_rcp_f32_e32 v154, v153
	v_lshl_add_u32 v150, s16, 8, v144
	v_mul_f32_e32 v124, v124, v151
	v_mul_f32_e32 v116, v124, v116
	v_mul_f32_e32 v124, v125, v154
	v_mul_f32_e32 v125, 0xbfb8aa3b, v126
	v_exp_f32_e32 v125, v125
	v_mul_f32_e32 v151, 0xbfb8aa3b, v127
	v_exp_f32_e32 v151, v151
	v_mul_f32_e32 v117, v124, v117
	v_add_f32_e32 v124, 1.0, v125
	v_rcp_f32_e32 v124, v124
	v_add_f32_e32 v125, 1.0, v151
	v_mul_f32_e32 v151, 0xbfb8aa3b, v120
	v_rcp_f32_e32 v125, v125
	v_exp_f32_e32 v151, v151
	v_mul_f32_e32 v124, v126, v124
	v_mul_f32_e32 v118, v124, v118
	v_mul_f32_e32 v124, v127, v125
	v_add_f32_e32 v125, 1.0, v151
	v_rcp_f32_e32 v125, v125
	v_mul_f32_e32 v126, 0xbfb8aa3b, v121
	v_exp_f32_e32 v126, v126
	v_mul_f32_e32 v119, v124, v119
	v_mul_f32_e32 v120, v120, v125
	v_mul_f32_e32 v112, v120, v112
	v_add_f32_e32 v120, 1.0, v126
	v_mul_f32_e32 v124, 0xbfb8aa3b, v122
	v_rcp_f32_e32 v120, v120
	v_exp_f32_e32 v124, v124
	v_mul_f32_e32 v125, 0xbfb8aa3b, v123
	v_exp_f32_e32 v125, v125
	v_mul_f32_e32 v120, v121, v120
	v_add_f32_e32 v121, 1.0, v124
	v_rcp_f32_e32 v121, v121
	v_add_f32_e32 v124, 1.0, v125
	v_rcp_f32_e32 v124, v124
	v_mul_f32_e32 v113, v120, v113
	v_mul_f32_e32 v120, v122, v121
	v_mul_f32_e32 v122, 0xbfb8aa3b, v108
	v_mul_f32_e32 v114, v120, v114
	v_mul_f32_e32 v120, v123, v124
	v_exp_f32_e32 v122, v122
	v_mul_f32_e32 v123, 0xbfb8aa3b, v109
	v_exp_f32_e32 v123, v123
	v_ashrrev_i32_e32 v153, 31, v152
	v_add_f32_e32 v122, 1.0, v122
	v_rcp_f32_e32 v122, v122
	v_add_f32_e32 v123, 1.0, v123
	v_rcp_f32_e32 v123, v123
	v_mul_f32_e32 v115, v120, v115
	v_cvt_pk_bf16_f32 v116, v116, v117
	v_cvt_pk_bf16_f32 v117, v118, v119
	v_cvt_pk_bf16_f32 v118, v112, v113
	v_mov_b64_e32 v[112:113], s[48:49]
	v_cvt_pk_bf16_f32 v119, v114, v115
	v_mad_i64_i32 v[120:121], s[18:19], v150, s38, v[112:113]
	v_lshlrev_b64 v[114:115], 1, v[152:153]
	v_mul_f32_e32 v108, v108, v122
	v_lshl_add_u64 v[120:121], v[120:121], 0, v[114:115]
	v_mul_f32_e32 v100, v108, v100
	v_mul_f32_e32 v108, v109, v123
	v_mul_f32_e32 v109, 0xbfb8aa3b, v110
	global_store_dwordx4 v[120:121], v[116:119], off
	v_exp_f32_e32 v109, v109
	v_mul_f32_e32 v101, v108, v101
	v_mul_f32_e32 v116, 0xbfb8aa3b, v111
	v_exp_f32_e32 v116, v116
	v_add_f32_e32 v108, 1.0, v109
	v_rcp_f32_e32 v108, v108
	s_andn2_b64 vcc, exec, s[2:3]
	v_add_f32_e32 v109, 1.0, v116
	v_mul_f32_e32 v116, 0xbfb8aa3b, v104
	v_rcp_f32_e32 v109, v109
	v_exp_f32_e32 v116, v116
	v_mul_f32_e32 v108, v110, v108
	v_mul_f32_e32 v102, v108, v102
	v_mul_f32_e32 v108, v111, v109
	v_add_f32_e32 v109, 1.0, v116
	v_rcp_f32_e32 v109, v109
	v_mul_f32_e32 v110, 0xbfb8aa3b, v105
	v_exp_f32_e32 v110, v110
	v_mul_f32_e32 v103, v108, v103
	v_mul_f32_e32 v104, v104, v109
	v_mul_f32_e32 v104, v104, v96
	v_add_f32_e32 v96, 1.0, v110
	v_mul_f32_e32 v108, 0xbfb8aa3b, v106
	v_rcp_f32_e32 v96, v96
	v_exp_f32_e32 v108, v108
	v_mul_f32_e32 v109, 0xbfb8aa3b, v107
	v_exp_f32_e32 v109, v109
	v_mul_f32_e32 v96, v105, v96
	v_add_f32_e32 v105, 1.0, v108
	v_rcp_f32_e32 v105, v105
	v_add_f32_e32 v108, 1.0, v109
	v_rcp_f32_e32 v108, v108
	v_mul_f32_e32 v109, v96, v97
	v_mul_f32_e32 v96, v106, v105
	v_mul_f32_e32 v105, v96, v98
	v_mul_f32_e32 v96, v107, v108
	v_mul_f32_e32 v99, v96, v99
	v_cvt_pk_bf16_f32 v96, v100, v101
	v_cvt_pk_bf16_f32 v97, v102, v103
	v_mul_f32_e32 v102, 0xbfb8aa3b, v92
	v_exp_f32_e32 v102, v102
	v_mul_f32_e32 v103, 0xbfb8aa3b, v93
	v_exp_f32_e32 v103, v103
	v_or_b32_e32 v106, 16, v150
	v_add_f32_e32 v102, 1.0, v102
	v_rcp_f32_e32 v102, v102
	v_add_f32_e32 v103, 1.0, v103
	v_rcp_f32_e32 v103, v103
	v_mad_i64_i32 v[100:101], s[18:19], v106, s38, v[112:113]
	v_mul_f32_e32 v92, v92, v102
	v_lshl_add_u64 v[100:101], v[100:101], 0, v[114:115]
	v_mul_f32_e32 v84, v92, v84
	v_mul_f32_e32 v92, v93, v103
	v_mul_f32_e32 v93, 0xbfb8aa3b, v94
	v_cvt_pk_bf16_f32 v98, v104, v109
	v_cvt_pk_bf16_f32 v99, v105, v99
	global_store_dwordx4 v[100:101], v[96:99], off
	v_exp_f32_e32 v93, v93
	v_mul_f32_e32 v85, v92, v85
	v_mul_f32_e32 v96, 0xbfb8aa3b, v95
	v_exp_f32_e32 v96, v96
	v_add_f32_e32 v92, 1.0, v93
	v_rcp_f32_e32 v92, v92
	s_mov_b64 s[2:3], -1
	v_add_f32_e32 v93, 1.0, v96
	v_mul_f32_e32 v96, 0xbfb8aa3b, v88
	v_rcp_f32_e32 v93, v93
	v_exp_f32_e32 v96, v96
	v_mul_f32_e32 v92, v94, v92
	v_mul_f32_e32 v86, v92, v86
	v_mul_f32_e32 v92, v95, v93
	v_add_f32_e32 v93, 1.0, v96
	v_rcp_f32_e32 v93, v93
	v_mul_f32_e32 v94, 0xbfb8aa3b, v89
	v_exp_f32_e32 v94, v94
	v_mul_f32_e32 v87, v92, v87
	v_mul_f32_e32 v88, v88, v93
	v_mul_f32_e32 v88, v88, v80
	v_add_f32_e32 v80, 1.0, v94
	v_mul_f32_e32 v92, 0xbfb8aa3b, v90
	v_rcp_f32_e32 v80, v80
	v_exp_f32_e32 v92, v92
	v_mul_f32_e32 v93, 0xbfb8aa3b, v91
	v_exp_f32_e32 v93, v93
	v_mul_f32_e32 v80, v89, v80
	v_add_f32_e32 v89, 1.0, v92
	v_rcp_f32_e32 v89, v89
	v_add_f32_e32 v92, 1.0, v93
	v_rcp_f32_e32 v92, v92
	v_mul_f32_e32 v93, v80, v81
	v_mul_f32_e32 v80, v90, v89
	v_mul_f32_e32 v89, v80, v82
	v_mul_f32_e32 v80, v91, v92
	v_mul_f32_e32 v83, v80, v83
	v_cvt_pk_bf16_f32 v80, v84, v85
	v_cvt_pk_bf16_f32 v81, v86, v87
	v_mul_f32_e32 v86, 0xbfb8aa3b, v76
	v_exp_f32_e32 v86, v86
	v_mul_f32_e32 v87, 0xbfb8aa3b, v77
	v_exp_f32_e32 v87, v87
	v_or_b32_e32 v90, 32, v150
	v_add_f32_e32 v86, 1.0, v86
	v_rcp_f32_e32 v86, v86
	v_add_f32_e32 v87, 1.0, v87
	v_rcp_f32_e32 v87, v87
	v_mad_i64_i32 v[84:85], s[18:19], v90, s38, v[112:113]
	v_mul_f32_e32 v76, v76, v86
	v_lshl_add_u64 v[84:85], v[84:85], 0, v[114:115]
	v_mul_f32_e32 v68, v76, v68
	v_mul_f32_e32 v76, v77, v87
	v_mul_f32_e32 v77, 0xbfb8aa3b, v78
	v_cvt_pk_bf16_f32 v82, v88, v93
	v_cvt_pk_bf16_f32 v83, v89, v83
	global_store_dwordx4 v[84:85], v[80:83], off
	v_exp_f32_e32 v77, v77
	v_mul_f32_e32 v69, v76, v69
	v_mul_f32_e32 v80, 0xbfb8aa3b, v79
	v_exp_f32_e32 v80, v80
	v_add_f32_e32 v76, 1.0, v77
	v_rcp_f32_e32 v76, v76
	v_add_f32_e32 v77, 1.0, v80
	v_mul_f32_e32 v80, 0xbfb8aa3b, v72
	v_rcp_f32_e32 v77, v77
	v_exp_f32_e32 v80, v80
	v_mul_f32_e32 v76, v78, v76
	v_mul_f32_e32 v70, v76, v70
	v_mul_f32_e32 v76, v79, v77
	v_add_f32_e32 v77, 1.0, v80
	v_rcp_f32_e32 v77, v77
	v_mul_f32_e32 v78, 0xbfb8aa3b, v73
	v_exp_f32_e32 v78, v78
	v_mul_f32_e32 v71, v76, v71
	v_mul_f32_e32 v72, v72, v77
	v_mul_f32_e32 v72, v72, v64
	v_add_f32_e32 v64, 1.0, v78
	v_mul_f32_e32 v76, 0xbfb8aa3b, v74
	v_rcp_f32_e32 v64, v64
	v_exp_f32_e32 v76, v76
	v_mul_f32_e32 v77, 0xbfb8aa3b, v75
	v_exp_f32_e32 v77, v77
	v_mul_f32_e32 v64, v73, v64
	v_add_f32_e32 v73, 1.0, v76
	v_rcp_f32_e32 v73, v73
	v_add_f32_e32 v76, 1.0, v77
	v_rcp_f32_e32 v76, v76
	v_mul_f32_e32 v77, v64, v65
	v_mul_f32_e32 v64, v74, v73
	v_mul_f32_e32 v73, v64, v66
	v_mul_f32_e32 v64, v75, v76
	v_mul_f32_e32 v67, v64, v67
	v_cvt_pk_bf16_f32 v64, v68, v69
	v_cvt_pk_bf16_f32 v65, v70, v71
	v_mul_f32_e32 v70, 0xbfb8aa3b, v60
	v_exp_f32_e32 v70, v70
	v_mul_f32_e32 v71, 0xbfb8aa3b, v61
	v_or_b32_e32 v74, 48, v150
	v_exp_f32_e32 v71, v71
	v_mad_i64_i32 v[68:69], s[18:19], v74, s38, v[112:113]
	v_lshl_add_u64 v[68:69], v[68:69], 0, v[114:115]
	v_cvt_pk_bf16_f32 v66, v72, v77
	v_cvt_pk_bf16_f32 v67, v73, v67
	global_store_dwordx4 v[68:69], v[64:67], off
	s_nop 1
	v_add_f32_e32 v64, 1.0, v70
	v_rcp_f32_e32 v64, v64
	v_add_f32_e32 v65, 1.0, v71
	v_rcp_f32_e32 v65, v65
	v_add_u32_e32 v66, 0x80, v150
	v_mul_f32_e32 v60, v60, v64
	v_mul_f32_e32 v52, v60, v52
	v_mul_f32_e32 v60, v61, v65
	v_mul_f32_e32 v61, 0xbfb8aa3b, v62
	v_exp_f32_e32 v61, v61
	v_mul_f32_e32 v64, 0xbfb8aa3b, v63
	v_exp_f32_e32 v64, v64
	v_mul_f32_e32 v53, v60, v53
	v_add_f32_e32 v60, 1.0, v61
	v_rcp_f32_e32 v60, v60
	v_add_f32_e32 v61, 1.0, v64
	v_mul_f32_e32 v64, 0xbfb8aa3b, v56
	v_rcp_f32_e32 v61, v61
	v_exp_f32_e32 v64, v64
	v_mul_f32_e32 v60, v62, v60
	v_mul_f32_e32 v54, v60, v54
	v_mul_f32_e32 v60, v63, v61
	v_add_f32_e32 v61, 1.0, v64
	v_rcp_f32_e32 v61, v61
	v_mul_f32_e32 v62, 0xbfb8aa3b, v57
	v_exp_f32_e32 v62, v62
	v_mul_f32_e32 v55, v60, v55
	v_mul_f32_e32 v56, v56, v61
	v_mul_f32_e32 v56, v56, v48
	v_add_f32_e32 v48, 1.0, v62
	v_mul_f32_e32 v60, 0xbfb8aa3b, v58
	v_rcp_f32_e32 v48, v48
	v_exp_f32_e32 v60, v60
	v_mul_f32_e32 v61, 0xbfb8aa3b, v59
	v_exp_f32_e32 v61, v61
	v_mul_f32_e32 v48, v57, v48
	v_add_f32_e32 v57, 1.0, v60
	v_rcp_f32_e32 v57, v57
	v_add_f32_e32 v60, 1.0, v61
	v_rcp_f32_e32 v60, v60
	v_mul_f32_e32 v61, v48, v49
	v_mul_f32_e32 v48, v58, v57
	v_mul_f32_e32 v57, v48, v50
	v_mul_f32_e32 v48, v59, v60
	v_mul_f32_e32 v51, v48, v51
	v_cvt_pk_bf16_f32 v48, v52, v53
	v_cvt_pk_bf16_f32 v49, v54, v55
	v_mul_f32_e32 v54, 0xbfb8aa3b, v44
	v_exp_f32_e32 v54, v54
	v_mul_f32_e32 v55, 0xbfb8aa3b, v45
	v_exp_f32_e32 v55, v55
	v_mad_i64_i32 v[52:53], s[18:19], v66, s38, v[112:113]
	v_add_f32_e32 v54, 1.0, v54
	v_rcp_f32_e32 v54, v54
	v_add_f32_e32 v55, 1.0, v55
	v_rcp_f32_e32 v55, v55
	v_lshl_add_u64 v[52:53], v[52:53], 0, v[114:115]
	v_mul_f32_e32 v44, v44, v54
	v_mul_f32_e32 v36, v44, v36
	v_mul_f32_e32 v44, v45, v55
	v_mul_f32_e32 v45, 0xbfb8aa3b, v46
	v_cvt_pk_bf16_f32 v50, v56, v61
	v_cvt_pk_bf16_f32 v51, v57, v51
	global_store_dwordx4 v[52:53], v[48:51], off
	v_exp_f32_e32 v45, v45
	v_mul_f32_e32 v37, v44, v37
	v_mul_f32_e32 v48, 0xbfb8aa3b, v47
	v_exp_f32_e32 v48, v48
	v_add_f32_e32 v44, 1.0, v45
	v_rcp_f32_e32 v44, v44
	v_add_f32_e32 v45, 1.0, v48
	v_mul_f32_e32 v48, 0xbfb8aa3b, v40
	v_rcp_f32_e32 v45, v45
	v_exp_f32_e32 v48, v48
	v_mul_f32_e32 v44, v46, v44
	v_mul_f32_e32 v38, v44, v38
	v_mul_f32_e32 v44, v47, v45
	v_add_f32_e32 v45, 1.0, v48
	v_rcp_f32_e32 v45, v45
	v_mul_f32_e32 v46, 0xbfb8aa3b, v41
	v_exp_f32_e32 v46, v46
	v_mul_f32_e32 v39, v44, v39
	v_mul_f32_e32 v40, v40, v45
	v_mul_f32_e32 v40, v40, v32
	v_add_f32_e32 v32, 1.0, v46
	v_mul_f32_e32 v44, 0xbfb8aa3b, v42
	v_rcp_f32_e32 v32, v32
	v_exp_f32_e32 v44, v44
	v_mul_f32_e32 v45, 0xbfb8aa3b, v43
	v_exp_f32_e32 v45, v45
	v_mul_f32_e32 v32, v41, v32
	v_add_f32_e32 v41, 1.0, v44
	v_rcp_f32_e32 v41, v41
	v_add_f32_e32 v44, 1.0, v45
	v_rcp_f32_e32 v44, v44
	v_mul_f32_e32 v45, v32, v33
	v_mul_f32_e32 v32, v42, v41
	v_mul_f32_e32 v41, v32, v34
	v_mul_f32_e32 v32, v43, v44
	v_mul_f32_e32 v35, v32, v35
	v_cvt_pk_bf16_f32 v32, v36, v37
	v_cvt_pk_bf16_f32 v33, v38, v39
	v_mul_f32_e32 v38, 0xbfb8aa3b, v28
	v_exp_f32_e32 v38, v38
	v_mul_f32_e32 v39, 0xbfb8aa3b, v29
	v_exp_f32_e32 v39, v39
	v_add_u32_e32 v42, 0x90, v150
	v_add_f32_e32 v38, 1.0, v38
	v_rcp_f32_e32 v38, v38
	v_add_f32_e32 v39, 1.0, v39
	v_rcp_f32_e32 v39, v39
	v_mad_i64_i32 v[36:37], s[18:19], v42, s38, v[112:113]
	v_mul_f32_e32 v28, v28, v38
	v_lshl_add_u64 v[36:37], v[36:37], 0, v[114:115]
	v_mul_f32_e32 v20, v28, v20
	v_mul_f32_e32 v28, v29, v39
	v_mul_f32_e32 v29, 0xbfb8aa3b, v30
	v_cvt_pk_bf16_f32 v34, v40, v45
	v_cvt_pk_bf16_f32 v35, v41, v35
	global_store_dwordx4 v[36:37], v[32:35], off
	v_exp_f32_e32 v29, v29
	v_mul_f32_e32 v21, v28, v21
	v_mul_f32_e32 v32, 0xbfb8aa3b, v31
	v_exp_f32_e32 v32, v32
	v_add_f32_e32 v28, 1.0, v29
	v_rcp_f32_e32 v28, v28
	v_add_f32_e32 v29, 1.0, v32
	v_mul_f32_e32 v32, 0xbfb8aa3b, v24
	v_rcp_f32_e32 v29, v29
	v_exp_f32_e32 v32, v32
	v_mul_f32_e32 v28, v30, v28
	v_mul_f32_e32 v22, v28, v22
	v_mul_f32_e32 v28, v31, v29
	v_add_f32_e32 v29, 1.0, v32
	v_rcp_f32_e32 v29, v29
	v_mul_f32_e32 v30, 0xbfb8aa3b, v25
	v_exp_f32_e32 v30, v30
	v_mul_f32_e32 v23, v28, v23
	v_mul_f32_e32 v24, v24, v29
	v_mul_f32_e32 v24, v24, v16
	v_add_f32_e32 v16, 1.0, v30
	v_mul_f32_e32 v28, 0xbfb8aa3b, v26
	v_rcp_f32_e32 v16, v16
	v_exp_f32_e32 v28, v28
	v_mul_f32_e32 v29, 0xbfb8aa3b, v27
	v_exp_f32_e32 v29, v29
	v_mul_f32_e32 v16, v25, v16
	v_add_f32_e32 v25, 1.0, v28
	v_rcp_f32_e32 v25, v25
	v_add_f32_e32 v28, 1.0, v29
	v_rcp_f32_e32 v28, v28
	v_mul_f32_e32 v29, v16, v17
	v_mul_f32_e32 v16, v26, v25
	v_mul_f32_e32 v25, v16, v18
	v_mul_f32_e32 v16, v27, v28
	v_mul_f32_e32 v19, v16, v19
	v_cvt_pk_bf16_f32 v16, v20, v21
	v_cvt_pk_bf16_f32 v17, v22, v23
	v_mul_f32_e32 v22, 0xbfb8aa3b, v12
	v_exp_f32_e32 v22, v22
	v_mul_f32_e32 v23, 0xbfb8aa3b, v13
	v_exp_f32_e32 v23, v23
	v_add_u32_e32 v26, 0xa0, v150
	v_add_f32_e32 v22, 1.0, v22
	v_rcp_f32_e32 v22, v22
	v_add_f32_e32 v23, 1.0, v23
	v_rcp_f32_e32 v23, v23
	v_mad_i64_i32 v[20:21], s[18:19], v26, s38, v[112:113]
	v_mul_f32_e32 v12, v12, v22
	v_lshl_add_u64 v[20:21], v[20:21], 0, v[114:115]
	v_mul_f32_e32 v4, v12, v4
	v_mul_f32_e32 v12, v13, v23
	v_mul_f32_e32 v13, 0xbfb8aa3b, v14
	v_cvt_pk_bf16_f32 v18, v24, v29
	v_cvt_pk_bf16_f32 v19, v25, v19
	global_store_dwordx4 v[20:21], v[16:19], off
	v_exp_f32_e32 v13, v13
	v_mul_f32_e32 v5, v12, v5
	v_mul_f32_e32 v16, 0xbfb8aa3b, v15
	v_exp_f32_e32 v16, v16
	v_add_f32_e32 v12, 1.0, v13
	v_rcp_f32_e32 v12, v12
	v_add_f32_e32 v13, 1.0, v16
	v_mul_f32_e32 v16, 0xbfb8aa3b, v8
	v_rcp_f32_e32 v13, v13
	v_exp_f32_e32 v16, v16
	v_mul_f32_e32 v12, v14, v12
	v_mul_f32_e32 v6, v12, v6
	v_mul_f32_e32 v12, v15, v13
	v_add_f32_e32 v13, 1.0, v16
	v_rcp_f32_e32 v13, v13
	v_mul_f32_e32 v14, 0xbfb8aa3b, v9
	v_exp_f32_e32 v14, v14
	v_mul_f32_e32 v7, v12, v7
	v_mul_f32_e32 v8, v8, v13
	v_mul_f32_e32 v8, v8, v0
	v_add_f32_e32 v0, 1.0, v14
	v_mul_f32_e32 v12, 0xbfb8aa3b, v10
	v_rcp_f32_e32 v0, v0
	v_exp_f32_e32 v12, v12
	v_mul_f32_e32 v13, 0xbfb8aa3b, v11
	v_exp_f32_e32 v13, v13
	v_mul_f32_e32 v0, v9, v0
	v_add_f32_e32 v9, 1.0, v12
	v_rcp_f32_e32 v9, v9
	v_add_f32_e32 v12, 1.0, v13
	v_rcp_f32_e32 v12, v12
	v_mul_f32_e32 v13, v0, v1
	v_mul_f32_e32 v0, v10, v9
	v_mul_f32_e32 v9, v0, v2
	v_mul_f32_e32 v0, v11, v12
	v_add_u32_e32 v10, 0xb0, v150
	v_mul_f32_e32 v3, v0, v3
	v_cvt_pk_bf16_f32 v0, v4, v5
	v_mad_i64_i32 v[4:5], s[18:19], v10, s38, v[112:113]
	v_lshl_add_u64 v[4:5], v[4:5], 0, v[114:115]
	v_cvt_pk_bf16_f32 v1, v6, v7
	v_cvt_pk_bf16_f32 v2, v8, v13
	v_cvt_pk_bf16_f32 v3, v9, v3
	global_store_dwordx4 v[4:5], v[0:3], off
	s_cbranch_vccnz .LBB0_877
	s_andn2_b64 vcc, exec, s[0:1]
	s_cbranch_vccnz .LBB0_876
	s_nop 0
	s_branch .LBB0_876
.LBB0_887:
	s_waitcnt vmcnt(0)
	s_and_b64 vcc, exec, s[6:7]
	s_cbranch_vccz .Lp7_nb
	s_barrier
.Lp7_nb:
	s_barrier
.LBB0_888:
	s_cmp_lt_i32 s91, 9
	s_cbranch_scc1 .LBB0_938
	s_waitcnt vmcnt(0)
	s_waitcnt vmcnt(0)
	s_barrier
	s_and_saveexec_b64 s[0:1], s[92:93]
	s_cbranch_execz .LBB0_937
	s_add_i32 s2, 0, 0x20088
	v_mov_b32_e32 v0, s2
	ds_read_b32 v3, v0
	s_waitcnt lgkmcnt(0)
	v_readfirstlane_b32 s3, v3
	s_cmp_eq_u32 s3, 1
	s_cbranch_scc0 .Lsd7_slow
